# NSA selected phase: balanced static partition of the 96 item groups of a batch over its 32 workgroups (no queue atomics, the greedy descending queue ended ~9% above the mean)
# speedup vs baseline: 1.0068x; 1.0006x over previous
;   unsigned char* blut = (unsigned char*)lds; float* tbl = (float*)(lds + 4096);
;   build_lut(blut, tbl, p.in[I_RELB]);
;   unsigned* ctr = (unsigned*)(p.ws + OFF_MISC) + layer * 2 + 1 + rep * 8;
;   for (;;) {
.LBB0_700:
	s_or_b64 exec, exec, s[8:9]
	v_readlane_b32 s10, v254, 1
	s_and_b32 s10, s10, 7
	s_mul_i32 s101, s10, 6
	s_lshl_b32 s10, s10, 2
	s_lshl_b32 s11, s47, 5
	s_add_u32 s10, s10, s11
	s_add_u32 s10, s10, 0x65c0080
	s_add_u32 s10, s34, s10
	s_addc_u32 s11, s35, 0
	v_readlane_b32 s8, v254, 1
	s_lshr_b32 s8, s8, 3
	s_mov_b32 s9, -1
	s_cmp_eq_u32 s8, 0
	s_cselect_b32 s9, 0xff3c3521, s9
	s_cmp_eq_u32 s8, 1
	s_cselect_b32 s9, 0xff443d0d, s9
	s_cmp_eq_u32 s8, 2
	s_cselect_b32 s9, 0xff434206, s9
	s_cmp_eq_u32 s8, 3
	s_cselect_b32 s9, 0xff403916, s9
	s_cmp_eq_u32 s8, 4
	s_cselect_b32 s9, 0xff5c3104, s9
	s_cmp_eq_u32 s8, 5
	s_cselect_b32 s9, 0xff573700, s9
	s_cmp_eq_u32 s8, 6
	s_cselect_b32 s9, 0xff413817, s9
	s_cmp_eq_u32 s8, 7
	s_cselect_b32 s9, 0xff463f08, s9
	s_cmp_eq_u32 s8, 8
	s_cselect_b32 s9, 0xff453a0e, s9
	s_cmp_eq_u32 s8, 9
	s_cselect_b32 s9, 0xff473e09, s9
	s_cmp_eq_u32 s8, 10
	s_cselect_b32 s9, 0xff583202, s9
	s_cmp_eq_u32 s8, 11
	s_cselect_b32 s9, 0xff5b3001, s9
	s_cmp_eq_u32 s8, 12
	s_cselect_b32 s9, 0xff483411, s9
	s_cmp_eq_u32 s8, 13
	s_cselect_b32 s9, 0xff493b0b, s9
	s_cmp_eq_u32 s8, 14
	s_cselect_b32 s9, 0xff4a3310, s9
	s_cmp_eq_u32 s8, 15
	s_cselect_b32 s9, 0xff4b360f, s9
	s_cmp_eq_u32 s8, 16
	s_cselect_b32 s9, 0x5e5a2e0c, s9
	s_cmp_eq_u32 s8, 17
	s_cselect_b32 s9, 0xff592f07, s9
	s_cmp_eq_u32 s8, 18
	s_cselect_b32 s9, 0xff4c2c15, s9
	s_cmp_eq_u32 s8, 19
	s_cselect_b32 s9, 0xff4d2d14, s9
	s_cmp_eq_u32 s8, 20
	s_cselect_b32 s9, 0xff4e2a13, s9
	s_cmp_eq_u32 s8, 21
	s_cselect_b32 s9, 0xff4f2b12, s9
	s_cmp_eq_u32 s8, 22
	s_cselect_b32 s9, 0xffff2805, s9
	s_cmp_eq_u32 s8, 23
	s_cselect_b32 s9, 0xff5d290a, s9
	s_cmp_eq_u32 s8, 24
	s_cselect_b32 s9, 0xff542218, s9
	s_cmp_eq_u32 s8, 25
	s_cselect_b32 s9, 0xff512719, s9
	s_cmp_eq_u32 s8, 26
	s_cselect_b32 s9, 0xff52241a, s9
	s_cmp_eq_u32 s8, 27
	s_cselect_b32 s9, 0xff53251b, s9
	s_cmp_eq_u32 s8, 28
	s_cselect_b32 s9, 0xffff2603, s9
	s_cmp_eq_u32 s8, 29
	s_cselect_b32 s9, 0x5f56231d, s9
	s_cmp_eq_u32 s8, 30
	s_cselect_b32 s9, 0xff50201e, s9
	s_cmp_eq_u32 s8, 31
	s_cselect_b32 s9, 0xff551f1c, s9
	v_writelane_b32 v252, s9, 13
	s_mov_b64 s[54:55], 0
	s_waitcnt vmcnt(0) lgkmcnt(0)
	s_barrier
	s_branch .LBB0_703

;     ...
;   for (;;) {
;     const int item = wave_fetch(ctr);
;     if (item >= 128 * 48) break;
;     const int qb = 127 - item / 48, sub = item % 48;
.LBB0_703:
	s_cmp_eq_u32 s33, 0x100
	s_cbranch_scc0 .LfY_dyn
	v_readlane_b32 s8, v252, 13
	s_and_b32 s9, s8, 0xff
	s_lshr_b32 s8, s8, 8
	s_or_b32 s8, s8, 0xff000000
	v_writelane_b32 v252, s8, 13
	s_lshl_b32 s9, s9, 3
	v_lshrrev_b32_e32 v1, 6, v129
	v_add_u32_e32 v0, s9, v1
	s_branch .LfY_end

; #define TIDX get_tid_()
; DI float bf2f(bf16_t b) { return __uint_as_float(((unsigned)b) << 16); }
; DI int crow(int i, int h) { return (i & 3) + 8 * (i >> 2) + 4 * h; }
; DI void nsa_main_item(const Params& p, int b, int head, int qb, const unsigned char* blut, const float* tbl) {
;   const int lane = TIDX & 63, r = lane & 31, h = lane >> 5;
;   const int g = head / 3, bg = b * 2 + g;
;   const int t = qb * 32 + r;
;   const float* tblh = tbl + head * 32;
;   bf16x8 qf[4];
;   load_q(qf, (const bf16_t*)(p.ws + OFF_QN) + (size_t)(b * 4096 + t) * 384 + head * 64 + 8 * h);
;   const unsigned long long selm = ((const unsigned long long*)(p.ws + OFF_SELM))[(size_t)bg * 4096 + t];
;   const float* gates = (const float*)(p.ws + OFF_GATES) + (size_t)(b * 4096 + t) * 18 + head * 3;
;   const float g1 = gates[1];
;   f32x16 y0, y1;
;   {
;     const bf16_t* oc = (const bf16_t*)(p.ws + OFF_OC) + (size_t)(b * 4096 + t) * 384 + head * 64;
;     const bf16_t* yw = (const bf16_t*)(p.ws + OFF_Y) + (size_t)(b * 4096 + t) * 768 + head * 64;
; #pragma unroll
;     for (int i = 0; i < 16; ++i) { y0[i] = bf2f(oc[crow(i, h)]) + bf2f(yw[crow(i, h)]); y1[i] = bf2f(oc[32 + crow(i, h)]) + bf2f(yw[32 + crow(i, h)]); }
;   }
;   {
;     const bf16_t* K = (const bf16_t*)(p.ws + OFF_KSEL) + (size_t)bg * 4096 * 64;
;     const bf16_t* Vt = (const bf16_t*)(p.ws + OFF_VSELT) + (size_t)bg * 64 * 4096;
;     AttnSt st; attn_init(st);
;     attn_loop(st, qf, 0, qb, 32,
;       [&](int kt) { return K + (size_t)kt * 2048 + (h * 32 + r) * 8; },
;       [&](int kt) { return Vt + (size_t)kt * 2048 + (h * 32 + r) * 4; },
;       [&](int kt) { return __ballot((selm >> (kt >> 1)) & 1ull) != 0ull; },
;     ...
;   for (;;) {
;     const int item = wave_fetch(ctr);
;     if (item >= 128 * 48) break;
;     const int qb = 127 - item / 48, sub = item % 48;
;     nsa_main_item(p, sub / 6, sub % 6, qb, blut, tbl);
.LfY_end:
	s_movk_i32 s8, 0x300
	s_waitcnt lgkmcnt(0)
	v_cmp_gt_i32_e32 vcc, s8, v0
	s_mov_b64 s[8:9], -1
	s_and_saveexec_b64 s[14:15], vcc
	s_cbranch_execz .LBB0_702
	v_lshrrev_b32_e32 v1, 4, v0
	v_lshlrev_b32_e32 v1, 3, v1
	v_and_b32_e32 v2, 7, v0
	v_add_u32_e32 v1, v1, v2
	v_bfe_u32 v2, v0, 3, 1
	v_mul_u32_u24_e32 v2, 3, v2
	v_add_u32_e32 v2, v2, v1
	v_mul_u32_u24_e32 v0, 0x5556, v1
	v_lshrrev_b32_e32 v0, 16, v0
	v_mul_u32_u24_e32 v0, 45, v0
	v_add3_u32 v0, v0, v2, s101
	s_mov_b32 s8, 0xd5555555
	v_mul_hi_i32 v1, v0, s8
	v_lshrrev_b32_e32 v2, 31, v1
	v_ashrrev_i32_e32 v1, 3, v1
	s_movk_i32 s8, 0x7f
	v_add3_u32 v217, v1, v2, s8
	s_mov_b32 s8, 0x2aaaaaab
	v_mul_hi_i32 v1, v0, s8
	v_lshrrev_b32_e32 v2, 31, v1
	v_lshrrev_b32_e32 v1, 3, v1
	v_add_u32_e32 v1, v1, v2
	v_mul_lo_u32 v1, v1, 48
	v_sub_u32_e32 v0, v0, v1
	v_mul_lo_u16_e32 v1, 43, v0
	v_lshrrev_b16_e32 v2, 15, v1
	v_add_u16_sdwa v1, v1, v2 dst_sel:DWORD dst_unused:UNUSED_PAD src0_sel:BYTE_1 src1_sel:DWORD
	v_bfe_i32 v2, v1, 0, 8
	v_mul_lo_u16_e32 v1, 6, v1
	v_sub_u16_e32 v0, v0, v1
	v_bfe_i32 v28, v0, 0, 8
	v_mov_b32_e32 v0, v129
	v_lshlrev_b32_e32 v31, 5, v217
	v_and_b32_e32 v29, 31, v0
	v_bfe_u32 v30, v0, 5, 1
	v_mul_lo_u16_e32 v0, 0x56, v28
	v_lshrrev_b16_e32 v1, 15, v0
	v_add_u16_sdwa v0, v0, v1 dst_sel:DWORD dst_unused:UNUSED_PAD src0_sel:BYTE_1 src1_sel:DWORD
	v_readlane_b32 s8, v253, 13
	v_bfe_i32 v0, v0, 0, 8
	v_or_b32_e32 v10, v29, v31
	v_readlane_b32 s9, v253, 14
	v_lshl_add_u32 v8, v2, 1, v0
	v_lshl_add_u32 v22, v2, 12, v10
	v_mov_b64_e32 v[0:1], s[8:9]
	s_movk_i32 s23, 0x300
	v_mad_i64_i32 v[0:1], s[8:9], v22, s23, v[0:1]
	v_lshlrev_b32_e32 v2, 6, v28
	v_ashrrev_i32_e32 v3, 31, v2
	v_readlane_b32 s8, v253, 23
	v_lshlrev_b64 v[2:3], 1, v[2:3]
	v_readlane_b32 s9, v253, 24
	v_lshl_add_u64 v[4:5], v[0:1], 0, v[2:3]
	v_lshlrev_b32_e32 v130, 3, v30
	v_mov_b64_e32 v[0:1], s[8:9]
	v_mad_i64_i32 v[0:1], s[8:9], v22, s23, v[0:1]
	v_readlane_b32 s8, v253, 19
	v_readlane_b32 s9, v253, 20
	v_lshl_add_u64 v[0:1], v[0:1], 0, v[2:3]
	v_ashrrev_i32_e32 v9, 31, v8
	v_mov_b64_e32 v[6:7], s[8:9]
	s_movk_i32 s8, 0x600
	v_mad_i64_i32 v[6:7], s[8:9], v22, s8, v[6:7]
	v_lshl_add_u64 v[2:3], v[6:7], 0, v[2:3]
	v_lshl_add_u64 v[12:13], v[0:1], 0, v[130:131]
	v_readlane_b32 s8, v253, 25
	v_lshlrev_b32_e32 v0, 3, v29
	v_lshl_add_u64 v[132:133], v[2:3], 0, v[130:131]
	v_lshlrev_b64 v[14:15], 19, v[8:9]
	v_readlane_b32 s9, v253, 26
	v_lshl_or_b32 v130, v30, 8, v0
	v_lshlrev_b32_e32 v20, 1, v130
	v_lshl_add_u64 v[16:17], s[8:9], 0, v[14:15]
	v_mov_b32_e32 v21, v131
	v_lshl_add_u64 v[148:149], v[16:17], 0, v[20:21]
	global_load_dwordx4 v[0:3], v[148:149], off
	v_lshlrev_b32_e32 v6, 4, v30
	v_mov_b32_e32 v7, v131
	v_lshl_add_u64 v[4:5], v[4:5], 0, v[6:7]
	global_load_dwordx4 v[80:83], v[4:5], off
	v_mov_b64_e32 v[6:7], s[34:35]
	s_movk_i32 s8, 0x48
	v_mad_i64_i32 v[6:7], s[8:9], v22, s8, v[6:7]
	v_mul_i32_i24_e32 v22, 3, v28
	v_ashrrev_i32_e32 v23, 31, v22
	v_cmp_eq_u32_e32 vcc, 0, v217
	v_lshl_add_u64 v[6:7], v[22:23], 2, v[6:7]
	s_mov_b32 s8, 0x165c4000
	v_cndmask_b32_e64 v18, v197, 0, vcc
	v_add_co_u32_e32 v22, vcc, s8, v6
	v_readlane_b32 s8, v253, 21
	s_nop 0
	v_addc_co_u32_e32 v23, vcc, 0, v7, vcc
	global_load_dwordx4 v[84:87], v[4:5], off offset:32
	global_load_dwordx4 v[88:91], v[4:5], off offset:64
	global_load_dwordx4 v[92:95], v[4:5], off offset:96
	global_load_dwordx2 v[136:137], v[12:13], off offset:64
	global_load_dwordx2 v[144:145], v[12:13], off offset:80
	global_load_dwordx2 v[150:151], v[12:13], off offset:32
	global_load_dwordx2 v[160:161], v[12:13], off offset:48
	global_load_dwordx2 v[134:135], v[132:133], off
	global_load_dwordx2 v[142:143], v[132:133], off offset:16
	global_load_dwordx2 v[152:153], v[132:133], off offset:32
	global_load_dwordx2 v[162:163], v[132:133], off offset:48
	global_load_dwordx2 v[154:155], v[12:13], off offset:96
	global_load_dwordx2 v[164:165], v[12:13], off offset:112
	global_load_dwordx4 v[4:7], v[148:149], off offset:1024
	global_load_dwordx2 v[138:139], v[132:133], off offset:64
	global_load_dwordx2 v[146:147], v[132:133], off offset:80
	global_load_dwordx2 v[158:159], v[132:133], off offset:96
	global_load_dwordx2 v[166:167], v[132:133], off offset:112
	v_lshlrev_b64 v[8:9], 15, v[8:9]
	v_readlane_b32 s9, v253, 22
	v_mov_b32_e32 v11, v131
	v_mov_b32_e32 v19, v131
	v_lshl_add_u64 v[8:9], s[8:9], 0, v[8:9]
	v_lshl_add_u64 v[24:25], v[10:11], 3, v[8:9]
	v_lshl_add_u64 v[26:27], v[16:17], 0, v[18:19]
	global_load_dwordx4 v[8:11], v[148:149], off offset:2048
	global_load_dwordx2 v[168:169], v[24:25], off
	global_load_dword v218, v[22:23], off offset:4
	global_load_dwordx2 v[140:141], v[12:13], off
	global_load_dwordx2 v[156:157], v[12:13], off offset:16
	global_load_dwordx4 v[16:19], v[148:149], off offset:3072
	v_readlane_b32 s8, v253, 27
	v_readlane_b32 s9, v253, 28
	v_lshl_add_u64 v[12:13], v[26:27], 0, v[20:21]
	global_load_dwordx4 v[108:111], v[12:13], off offset:3072
	global_load_dwordx4 v[104:107], v[12:13], off offset:2048
	global_load_dwordx4 v[100:103], v[12:13], off offset:1024
	global_load_dwordx4 v[96:99], v[12:13], off
	v_lshl_add_u64 v[14:15], s[8:9], 0, v[14:15]
	v_lshl_add_u64 v[170:171], v[14:15], 0, v[130:131]
	global_load_dwordx2 v[114:115], v[170:171], off offset:3584
	global_load_dwordx2 v[112:113], v[170:171], off offset:3072
	global_load_dwordx2 v[118:119], v[170:171], off offset:2560
	global_load_dwordx2 v[116:117], v[170:171], off offset:2048
	global_load_dwordx2 v[122:123], v[170:171], off offset:1536
	global_load_dwordx2 v[120:121], v[170:171], off offset:1024
	global_load_dwordx2 v[126:127], v[170:171], off offset:512
	global_load_dwordx2 v[124:125], v[170:171], off
	s_mov_b32 s56, 0
	s_mov_b32 s57, s56
	s_mov_b32 s58, s56
	s_mov_b32 s59, s56
	s_mov_b32 s60, s56
	s_mov_b32 s61, s56
	s_mov_b32 s62, s56
	s_mov_b32 s63, s56
	s_mov_b32 s64, s56
	s_mov_b32 s65, s56
	s_mov_b32 s66, s56
	s_mov_b32 s67, s56
	s_mov_b32 s68, s56
	s_mov_b32 s69, s56
	s_waitcnt vmcnt(36)
; #define TIDX get_tid_()
; DI float bf2f(bf16_t b) { return __uint_as_float(((unsigned)b) << 16); }
; DI int crow(int i, int h) { return (i & 3) + 8 * (i >> 2) + 4 * h; }
; DI void nsa_main_item(const Params& p, int b, int head, int qb, const unsigned char* blut, const float* tbl) {
;   const int lane = TIDX & 63, r = lane & 31, h = lane >> 5;
;   const int g = head / 3, bg = b * 2 + g;
;   const int t = qb * 32 + r;
;   const float* tblh = tbl + head * 32;
;   bf16x8 qf[4];
;   load_q(qf, (const bf16_t*)(p.ws + OFF_QN) + (size_t)(b * 4096 + t) * 384 + head * 64 + 8 * h);
;   const unsigned long long selm = ((const unsigned long long*)(p.ws + OFF_SELM))[(size_t)bg * 4096 + t];
;   const float* gates = (const float*)(p.ws + OFF_GATES) + (size_t)(b * 4096 + t) * 18 + head * 3;
;   const float g1 = gates[1];
;   f32x16 y0, y1;
;   {
;     const bf16_t* oc = (const bf16_t*)(p.ws + OFF_OC) + (size_t)(b * 4096 + t) * 384 + head * 64;
;     const bf16_t* yw = (const bf16_t*)(p.ws + OFF_Y) + (size_t)(b * 4096 + t) * 768 + head * 64;
; #pragma unroll
;     for (int i = 0; i < 16; ++i) { y0[i] = bf2f(oc[crow(i, h)]) + bf2f(yw[crow(i, h)]); y1[i] = bf2f(oc[32 + crow(i, h)]) + bf2f(yw[32 + crow(i, h)]); }
;   }
;   {
;     const bf16_t* K = (const bf16_t*)(p.ws + OFF_KSEL) + (size_t)bg * 4096 * 64;
;     const bf16_t* Vt = (const bf16_t*)(p.ws + OFF_VSELT) + (size_t)bg * 64 * 4096;
;     AttnSt st; attn_init(st);
;     attn_loop(st, qf, 0, qb, 32,
	v_mfma_f32_32x32x16_bf16 v[48:63], v[0:3], v[80:83], 0
	s_mov_b32 s70, s56
	s_mov_b32 s71, s56
	v_lshlrev_b32_e32 v20, 2, v30
	v_lshl_add_u32 v219, v28, 7, 0
	v_subrev_u32_e32 v220, 31, v31
	v_sub_u32_e32 v221, v29, v20
	v_mov_b32_e32 v222, 0
	s_waitcnt vmcnt(22)
	v_mfma_f32_32x32x16_bf16 v[48:63], v[4:7], v[84:87], v[48:63]
	v_mov_b32_e32 v223, 0xff800000
	s_waitcnt vmcnt(17)
	v_mfma_f32_32x32x16_bf16 v[48:63], v[8:11], v[88:91], v[48:63]
	v_mov_b64_e32 v[0:1], s[56:57]
	v_mov_b64_e32 v[14:15], s[70:71]
	v_mov_b64_e32 v[2:3], s[58:59]
	v_mov_b64_e32 v[4:5], s[60:61]
	v_mov_b64_e32 v[6:7], s[62:63]
	v_mov_b64_e32 v[8:9], s[64:65]
	v_mov_b64_e32 v[10:11], s[66:67]
	s_waitcnt vmcnt(12)
	v_mfma_f32_32x32x16_bf16 v[48:63], v[16:19], v[92:95], v[48:63]
	v_mov_b64_e32 v[12:13], s[68:69]
	v_mov_b64_e32 v[30:31], v[14:15]
	s_mov_b64 s[58:59], 0
	v_mov_b64_e32 v[28:29], v[12:13]
	v_mov_b64_e32 v[26:27], v[10:11]
	v_mov_b64_e32 v[24:25], v[8:9]
	v_mov_b64_e32 v[22:23], v[6:7]
	v_mov_b64_e32 v[20:21], v[4:5]
	v_mov_b64_e32 v[18:19], v[2:3]
	v_mov_b64_e32 v[16:17], v[0:1]
	s_waitcnt vmcnt(0)
	v_readfirstlane_b32 s60, v217
	v_lshrrev_b32_e32 v246, 6, v129
	v_and_b32_e32 v247, 63, v129
	v_lshlrev_b32_e32 v247, 3, v247
	v_readfirstlane_b32 s58, v246
	v_mov_b32_e32 v224, s60
	v_mov_b32_e32 v225, 0x1940
	v_lshl_add_u32 v234, v246, 2, v225
	ds_write_b32 v234, v224
	s_waitcnt lgkmcnt(0)
	s_barrier
	ds_read_b128 v[226:229], v225
	ds_read_b128 v[230:233], v225 offset:16
	s_waitcnt lgkmcnt(0)
	v_max3_u32 v226, v226, v227, v228
	v_max3_u32 v226, v226, v229, v230
	v_max3_u32 v226, v226, v231, v232
	v_max_u32_e32 v226, v226, v233
	s_nop 0
	v_readfirstlane_b32 s59, v226
	s_mov_b32 s56, 0
	s_mov_b32 s23, 0
	s_mov_b32 s100, 0x10000
	s_lshr_b32 s24, s59, 1
	s_min_u32 s24, s23, s24
	s_lshl_b32 s26, s24, 13
	s_lshl_b32 s24, s58, 10
	s_add_u32 s26, s26, s24
	s_mov_b32 s27, 0
	v_lshl_add_u64 v[248:249], v[148:149], 0, s[26:27]
	v_lshl_add_u64 v[250:251], v[170:171], 0, s[26:27]
	v_add_co_u32_e32 v250, vcc, v250, v247
	v_addc_co_u32_e32 v251, vcc, 0, v251, vcc
	s_add_u32 s24, s24, s100
	s_mov_b32 m0, s24
	s_nop 0
	global_load_lds_dwordx4 v[248:249], off
	s_add_u32 s24, s24, 0x2000
	s_mov_b32 m0, s24
	s_nop 0
	global_load_lds_dwordx4 v[250:251], off
	s_mov_b32 s23, 1
	s_mov_b32 s100, 0x14000
	s_lshr_b32 s24, s59, 1
	s_min_u32 s24, s23, s24
	s_lshl_b32 s26, s24, 13
	s_lshl_b32 s24, s58, 10
	s_add_u32 s26, s26, s24
	s_mov_b32 s27, 0
	v_lshl_add_u64 v[248:249], v[148:149], 0, s[26:27]
	v_lshl_add_u64 v[250:251], v[170:171], 0, s[26:27]
	v_add_co_u32_e32 v250, vcc, v250, v247
	v_addc_co_u32_e32 v251, vcc, 0, v251, vcc
	s_add_u32 s24, s24, s100
	s_mov_b32 m0, s24
	s_nop 0
	global_load_lds_dwordx4 v[248:249], off
	s_add_u32 s24, s24, 0x2000
	s_mov_b32 m0, s24
	s_nop 0
	global_load_lds_dwordx4 v[250:251], off
	s_mov_b32 s100, 0x10000
	v_lshrrev_b32_e32 v246, 6, v129
	v_mul_u32_u24_e32 v246, 6912, v246
	v_add_u32_e32 v242, 8192, v246
	v_and_b32_e32 v246, 63, v129
	v_add_u32_e32 v224, -64, v246
	v_mov_b32_e32 v224, 0
	v_mov_b32_e32 v225, v246
	v_add_u32_e32 v226, 64, v246
	v_add_u32_e32 v227, 128, v246
	v_add_u32_e32 v228, 192, v246
	v_add_u32_e32 v229, 256, v246
	v_add_u32_e32 v230, 320, v246
	v_add_u32_e32 v231, 384, v246
	v_add_u32_e32 v232, 448, v246
	ds_read_u8 v224, v224
	ds_read_u8 v225, v225
	ds_read_u8 v226, v226
	ds_read_u8 v227, v227
	ds_read_u8 v228, v228
	ds_read_u8 v229, v229
	ds_read_u8 v230, v230
	ds_read_u8 v231, v231
	ds_read_u8 v232, v232
	s_waitcnt lgkmcnt(8)
	v_lshl_add_u32 v224, v224, 2, v219
	s_waitcnt lgkmcnt(7)
	v_lshl_add_u32 v225, v225, 2, v219
	s_waitcnt lgkmcnt(6)
	v_lshl_add_u32 v226, v226, 2, v219
	s_waitcnt lgkmcnt(5)
	v_lshl_add_u32 v227, v227, 2, v219
	s_waitcnt lgkmcnt(4)
	v_lshl_add_u32 v228, v228, 2, v219
	s_waitcnt lgkmcnt(3)
	v_lshl_add_u32 v229, v229, 2, v219
	s_waitcnt lgkmcnt(2)
	v_lshl_add_u32 v230, v230, 2, v219
	s_waitcnt lgkmcnt(1)
	v_lshl_add_u32 v231, v231, 2, v219
	s_waitcnt lgkmcnt(0)
	v_lshl_add_u32 v232, v232, 2, v219
	ds_read_b32 v224, v224 offset:4096
	ds_read_b32 v225, v225 offset:4096
	ds_read_b32 v226, v226 offset:4096
	ds_read_b32 v227, v227 offset:4096
	ds_read_b32 v228, v228 offset:4096
	ds_read_b32 v229, v229 offset:4096
	ds_read_b32 v230, v230 offset:4096
	ds_read_b32 v231, v231 offset:4096
	ds_read_b32 v232, v232 offset:4096
	v_lshl_add_u32 v244, v246, 2, v242
	s_waitcnt lgkmcnt(8)
; DI void bias16(const unsigned char* blut, const float* tblh, const int (&dist)[16], float (&bv)[16]) {
;   int bk[16];
; #pragma unroll
;   for (int i = 0; i < 16; ++i) { const int d = dist[i] < 0 ? 0 : (dist[i] > 2048 ? 2048 : dist[i]); bk[i] = blut[d]; }
; #pragma unroll
;   for (int i = 0; i < 16; ++i) asm volatile("" : "+v"(bk[i]));
; #pragma unroll
;   for (int i = 0; i < 16; ++i) bv[i] = tblh[bk[i]];
; #pragma unroll
;   for (int i = 0; i < 16; ++i) asm volatile("" : "+v"(bv[i]));
; }
	ds_write_b32 v244, v224 offset:0
	s_waitcnt lgkmcnt(7)
	ds_write_b32 v244, v225 offset:256
	s_waitcnt lgkmcnt(6)
	ds_write_b32 v244, v226 offset:512
	s_waitcnt lgkmcnt(5)
	ds_write_b32 v244, v227 offset:768
	s_waitcnt lgkmcnt(4)
	ds_write_b32 v244, v228 offset:1024
	s_waitcnt lgkmcnt(3)
	ds_write_b32 v244, v229 offset:1280
	s_waitcnt lgkmcnt(2)
	ds_write_b32 v244, v230 offset:1536
	s_waitcnt lgkmcnt(1)
	ds_write_b32 v244, v231 offset:1792
	s_waitcnt lgkmcnt(0)
	ds_write_b32 v244, v232 offset:2048
	v_add_u32_e32 v224, 512, v246
	v_add_u32_e32 v225, 576, v246
	v_add_u32_e32 v226, 640, v246
	v_add_u32_e32 v227, 704, v246
	v_add_u32_e32 v228, 768, v246
	v_add_u32_e32 v229, 832, v246
	v_add_u32_e32 v230, 896, v246
	v_add_u32_e32 v231, 960, v246
	v_add_u32_e32 v232, 1024, v246
	ds_read_u8 v224, v224
	ds_read_u8 v225, v225
	ds_read_u8 v226, v226
	ds_read_u8 v227, v227
	ds_read_u8 v228, v228
	ds_read_u8 v229, v229
	ds_read_u8 v230, v230
	ds_read_u8 v231, v231
	ds_read_u8 v232, v232
	s_waitcnt lgkmcnt(8)
	v_lshl_add_u32 v224, v224, 2, v219
	s_waitcnt lgkmcnt(7)
	v_lshl_add_u32 v225, v225, 2, v219
	s_waitcnt lgkmcnt(6)
	v_lshl_add_u32 v226, v226, 2, v219
	s_waitcnt lgkmcnt(5)
	v_lshl_add_u32 v227, v227, 2, v219
	s_waitcnt lgkmcnt(4)
	v_lshl_add_u32 v228, v228, 2, v219
	s_waitcnt lgkmcnt(3)
	v_lshl_add_u32 v229, v229, 2, v219
	s_waitcnt lgkmcnt(2)
	v_lshl_add_u32 v230, v230, 2, v219
	s_waitcnt lgkmcnt(1)
	v_lshl_add_u32 v231, v231, 2, v219
	s_waitcnt lgkmcnt(0)
	v_lshl_add_u32 v232, v232, 2, v219
	ds_read_b32 v224, v224 offset:4096
	ds_read_b32 v225, v225 offset:4096
	ds_read_b32 v226, v226 offset:4096
	ds_read_b32 v227, v227 offset:4096
	ds_read_b32 v228, v228 offset:4096
	ds_read_b32 v229, v229 offset:4096
	ds_read_b32 v230, v230 offset:4096
	ds_read_b32 v231, v231 offset:4096
	ds_read_b32 v232, v232 offset:4096
	v_lshl_add_u32 v244, v246, 2, v242
	s_waitcnt lgkmcnt(8)
	ds_write_b32 v244, v224 offset:2304
	s_waitcnt lgkmcnt(7)
	ds_write_b32 v244, v225 offset:2560
	s_waitcnt lgkmcnt(6)
	ds_write_b32 v244, v226 offset:2816
	s_waitcnt lgkmcnt(5)
	ds_write_b32 v244, v227 offset:3072
	s_waitcnt lgkmcnt(4)
	ds_write_b32 v244, v228 offset:3328
	s_waitcnt lgkmcnt(3)
	ds_write_b32 v244, v229 offset:3584
	s_waitcnt lgkmcnt(2)
	ds_write_b32 v244, v230 offset:3840
	s_waitcnt lgkmcnt(1)
	ds_write_b32 v244, v231 offset:4096
	s_waitcnt lgkmcnt(0)
	ds_write_b32 v244, v232 offset:4352
	v_add_u32_e32 v224, 1088, v246
	v_add_u32_e32 v225, 1152, v246
	v_add_u32_e32 v226, 1216, v246
	v_add_u32_e32 v227, 1280, v246
	v_add_u32_e32 v228, 1344, v246
	v_add_u32_e32 v229, 1408, v246
	v_add_u32_e32 v230, 1472, v246
	v_add_u32_e32 v231, 1536, v246
	v_add_u32_e32 v232, 1600, v246
	ds_read_u8 v224, v224
	ds_read_u8 v225, v225
	ds_read_u8 v226, v226
	ds_read_u8 v227, v227
	ds_read_u8 v228, v228
	ds_read_u8 v229, v229
	ds_read_u8 v230, v230
	ds_read_u8 v231, v231
	ds_read_u8 v232, v232
	s_waitcnt lgkmcnt(8)
	v_lshl_add_u32 v224, v224, 2, v219
	s_waitcnt lgkmcnt(7)
	v_lshl_add_u32 v225, v225, 2, v219
	s_waitcnt lgkmcnt(6)
	v_lshl_add_u32 v226, v226, 2, v219
	s_waitcnt lgkmcnt(5)
	v_lshl_add_u32 v227, v227, 2, v219
	s_waitcnt lgkmcnt(4)
	v_lshl_add_u32 v228, v228, 2, v219
	s_waitcnt lgkmcnt(3)
	v_lshl_add_u32 v229, v229, 2, v219
	s_waitcnt lgkmcnt(2)
	v_lshl_add_u32 v230, v230, 2, v219
	s_waitcnt lgkmcnt(1)
	v_lshl_add_u32 v231, v231, 2, v219
	s_waitcnt lgkmcnt(0)
	v_lshl_add_u32 v232, v232, 2, v219
	ds_read_b32 v224, v224 offset:4096
	ds_read_b32 v225, v225 offset:4096
	ds_read_b32 v226, v226 offset:4096
	ds_read_b32 v227, v227 offset:4096
	ds_read_b32 v228, v228 offset:4096
	ds_read_b32 v229, v229 offset:4096
	ds_read_b32 v230, v230 offset:4096
	ds_read_b32 v231, v231 offset:4096
	ds_read_b32 v232, v232 offset:4096
	v_lshl_add_u32 v244, v246, 2, v242
	s_waitcnt lgkmcnt(8)
	ds_write_b32 v244, v224 offset:4608
	s_waitcnt lgkmcnt(7)
	ds_write_b32 v244, v225 offset:4864
	s_waitcnt lgkmcnt(6)
	ds_write_b32 v244, v226 offset:5120
	s_waitcnt lgkmcnt(5)
	ds_write_b32 v244, v227 offset:5376
	s_waitcnt lgkmcnt(4)
	ds_write_b32 v244, v228 offset:5632
	s_waitcnt lgkmcnt(3)
	ds_write_b32 v244, v229 offset:5888
	s_waitcnt lgkmcnt(2)
	ds_write_b32 v244, v230 offset:6144
	s_waitcnt lgkmcnt(1)
	ds_write_b32 v244, v231 offset:6400
	s_waitcnt lgkmcnt(0)
	ds_write_b32 v244, v232 offset:6656
	ds_read_b32 v240, v219 offset:4220
	v_add_u32_e32 v242, 148, v242
	v_mov_b32_e32 v243, 0x7f800000
	s_waitcnt lgkmcnt(0)
